# P6 epilogue: per-row sums of squares fetched at the tile header into unused LDS and read from LDS in the epilogue (no global round trip at the epilogue start); conv weights waited where first used
# speedup vs baseline: 1.0261x; 1.0002x over previous
.LBB0_2356:
	s_ashr_i32 s38, s58, 3
	s_add_i32 s38, s59, s38
	s_mul_hi_i32 s39, s38, 0x2e8ba2e9
	s_lshr_b32 s58, s39, 31
	s_ashr_i32 s65, s39, 5
	s_add_i32 s65, s65, s58
	s_lshl_b32 s85, s65, 3
	s_sub_i32 s39, 0x41, s85
	s_min_u32 s58, s39, 8
	s_mul_i32 s39, s65, 0xb0
	s_sub_i32 s59, s38, s39
	s_sext_i32_i16 s38, s59
	v_cvt_f32_ubyte0_e32 v3, s58
	v_cvt_f32_i32_e32 v2, s38
	v_rcp_iflag_f32_e32 v4, v3
	s_ashr_i32 s38, s38, 30
	s_or_b32 s60, s38, 1
	v_readfirstlane_b32 s61, v188
	v_mul_f32_e32 v4, v2, v4
	v_trunc_f32_e32 v4, v4
	v_fma_f32 v2, -v4, v3, v2
	v_cvt_i32_f32_e32 v4, v4
	v_cmp_ge_f32_e64 s[38:39], |v2|, v3
	s_and_b64 s[38:39], s[38:39], exec
	s_cselect_b32 s38, s60, 0
	v_readfirstlane_b32 s39, v4
	s_add_i32 s38, s39, s38
	s_sext_i32_i16 s64, s38
	s_mul_i32 s38, s38, s58
	s_sub_i32 s38, s59, s38
	s_sext_i32_i16 s66, s38
	s_lshl_b32 s58, s64, 8
	s_add_i32 s85, s85, s66
	s_ashr_i32 s59, s58, 31
	s_lshl_b32 s60, s85, 8
	v_and_b32_e32 v20, 0xff, v0
	v_lshlrev_b32_e32 v20, 2, v20
	s_lshl_b32 s38, s60, 2
	v_add_u32_e32 v21, s38, v20
	global_load_dword v22, v21, s[12:13]
	s_lshl_b64 s[38:39], s[58:59], 11
	s_add_u32 s62, s97, s38
	s_addc_u32 s63, s2, s39
	v_lshl_add_u64 v[4:5], s[62:63], 0, v[164:165]
	s_mov_b32 m0, s61
	v_readfirstlane_b32 s61, v189
	global_load_lds_dwordx4 v[4:5], off
	s_mov_b32 m0, s61
	s_ashr_i32 s61, s60, 31
	v_lshl_add_u64 v[2:3], s[62:63], 0, v[162:163]
	s_lshl_b64 s[62:63], s[60:61], 11
	s_add_u32 s62, s94, s62
	s_addc_u32 s63, s95, s63
	v_lshl_add_u64 v[8:9], s[62:63], 0, v[164:165]
	v_lshl_add_u64 v[6:7], s[62:63], 0, v[162:163]
	s_or_b32 s62, s58, 0x80
	s_ashr_i32 s63, s62, 31
	s_lshl_b64 s[62:63], s[62:63], 11
	s_add_u32 s62, s97, s62
	s_addc_u32 s63, s2, s63
	v_readfirstlane_b32 s61, v183
	v_lshl_add_u64 v[12:13], s[62:63], 0, v[164:165]
	v_lshl_add_u64 v[10:11], s[62:63], 0, v[162:163]
	s_or_b32 s62, s60, 0x80
	global_load_lds_dwordx4 v[2:3], off
	s_mov_b32 m0, s61
	v_readfirstlane_b32 s61, v184
	s_ashr_i32 s63, s62, 31
	global_load_lds_dwordx4 v[8:9], off
	s_mov_b32 m0, s61
	v_readfirstlane_b32 s61, v190
	s_lshl_b64 s[62:63], s[62:63], 11
	global_load_lds_dwordx4 v[6:7], off
	s_mov_b32 m0, s61
	v_readfirstlane_b32 s61, v191
	s_add_u32 s62, s94, s62
	global_load_lds_dwordx4 v[12:13], off
	s_mov_b32 m0, s61
	s_addc_u32 s63, s95, s63
	v_readfirstlane_b32 s61, v185
	global_load_lds_dwordx4 v[10:11], off
	v_lshl_add_u64 v[130:131], s[62:63], 0, v[164:165]
	s_mov_b32 m0, s61
	v_readfirstlane_b32 s61, v186
	global_load_lds_dwordx4 v[130:131], off
	v_lshl_add_u64 v[132:133], s[62:63], 0, v[162:163]
	s_mov_b32 m0, s61
	s_nop 0
	global_load_lds_dwordx4 v[132:133], off
	s_and_saveexec_b64 s[62:63], s[0:1]
	s_cbranch_execz .LBB0_2358
	s_barrier
.LBB0_2358:
	s_or_b64 exec, exec, s[62:63]
	v_add_u32_e32 v142, s72, v182
	v_add_u32_e32 v143, 0x2000, v142
	v_readfirstlane_b32 s61, v142
	v_lshl_add_u64 v[4:5], v[4:5], 0, s[16:17]
	s_mov_b32 m0, s61
	v_readfirstlane_b32 s61, v143
	v_add_u32_e32 v144, 0x8000, v183
	s_waitcnt vmcnt(4)
	v_add_u32_e32 v20, 0x20010, v20
	ds_write_b32 v20, v22
	s_barrier
	global_load_lds_dwordx4 v[4:5], off
	v_lshl_add_u64 v[2:3], v[2:3], 0, s[16:17]
	s_mov_b32 m0, s61
	v_readfirstlane_b32 s61, v144
	v_add_u32_e32 v145, 0xa000, v183
	global_load_lds_dwordx4 v[2:3], off
	v_lshl_add_u64 v[2:3], v[8:9], 0, s[16:17]
	s_mov_b32 m0, s61
	v_readfirstlane_b32 s61, v145
	v_add_u32_e32 v146, s73, v182
	global_load_lds_dwordx4 v[2:3], off
	v_lshl_add_u64 v[2:3], v[6:7], 0, s[16:17]
	s_mov_b32 m0, s61
	v_readfirstlane_b32 s61, v146
	v_add_u32_e32 v147, 0x2000, v146
	global_load_lds_dwordx4 v[2:3], off
	v_lshl_add_u64 v[2:3], v[12:13], 0, s[16:17]
	s_mov_b32 m0, s61
	v_readfirstlane_b32 s61, v147
	global_load_lds_dwordx4 v[2:3], off
	v_lshl_add_u64 v[2:3], v[10:11], 0, s[16:17]
	s_mov_b32 m0, s61
	v_lshl_add_u64 v[134:135], v[168:169], 0, s[38:39]
	global_load_lds_dwordx4 v[2:3], off
	v_lshl_add_u64 v[136:137], v[170:171], 0, s[38:39]
	s_lshl_b32 s38, s65, 11
	s_lshl_b32 s39, s66, 8
	s_add_i32 s38, s38, s39
	s_waitcnt vmcnt(6)
	s_ashr_i32 s39, s38, 31
	s_lshl_b64 s[62:63], s[38:39], 11
	v_mov_b32_e32 v2, 0
	v_lshl_add_u64 v[138:139], v[168:169], 0, s[62:63]
	v_lshl_add_u64 v[140:141], v[170:171], 0, s[62:63]
	s_mov_b32 s39, -2
	s_mov_b64 s[62:63], s[90:91]
	v_mov_b32_e32 v3, v2
	v_mov_b32_e32 v4, v2
	v_mov_b32_e32 v5, v2
	v_mov_b32_e32 v6, v2
	v_mov_b32_e32 v7, v2
	v_mov_b32_e32 v8, v2
	v_mov_b32_e32 v9, v2
	v_mov_b32_e32 v10, v2
	v_mov_b32_e32 v11, v2
	v_mov_b32_e32 v12, v2
	v_mov_b32_e32 v13, v2
	v_mov_b32_e32 v14, v2
	v_mov_b32_e32 v15, v2
	v_mov_b32_e32 v16, v2
	v_mov_b32_e32 v17, v2
	v_mov_b32_e32 v18, v2
	v_mov_b32_e32 v19, v2
	v_mov_b32_e32 v20, v2
	v_mov_b32_e32 v21, v2
	v_mov_b32_e32 v22, v2
	v_mov_b32_e32 v23, v2
	v_mov_b32_e32 v24, v2
	v_mov_b32_e32 v25, v2
	v_mov_b32_e32 v26, v2
	v_mov_b32_e32 v27, v2
	v_mov_b32_e32 v28, v2
	v_mov_b32_e32 v29, v2
	v_mov_b32_e32 v30, v2
	v_mov_b32_e32 v31, v2
	v_mov_b32_e32 v32, v2
	v_mov_b32_e32 v33, v2
	v_mov_b32_e32 v34, v2
	v_mov_b32_e32 v35, v2
	v_mov_b32_e32 v36, v2
	v_mov_b32_e32 v37, v2
	v_mov_b32_e32 v38, v2
	v_mov_b32_e32 v39, v2
	v_mov_b32_e32 v40, v2
	v_mov_b32_e32 v41, v2
	v_mov_b32_e32 v42, v2
	v_mov_b32_e32 v43, v2
	v_mov_b32_e32 v44, v2
	v_mov_b32_e32 v45, v2
	v_mov_b32_e32 v46, v2
	v_mov_b32_e32 v47, v2
	v_mov_b32_e32 v48, v2
	v_mov_b32_e32 v49, v2
	v_mov_b32_e32 v50, v2
	v_mov_b32_e32 v51, v2
	v_mov_b32_e32 v52, v2
	v_mov_b32_e32 v53, v2
	v_mov_b32_e32 v54, v2
	v_mov_b32_e32 v55, v2
	v_mov_b32_e32 v56, v2
	v_mov_b32_e32 v57, v2
	v_mov_b32_e32 v58, v2
	v_mov_b32_e32 v59, v2
	v_mov_b32_e32 v60, v2
	v_mov_b32_e32 v61, v2
	v_mov_b32_e32 v62, v2
	v_mov_b32_e32 v63, v2
	v_mov_b32_e32 v64, v2
	v_mov_b32_e32 v65, v2
	v_mov_b32_e32 v66, v2
	v_mov_b32_e32 v67, v2
	v_mov_b32_e32 v68, v2
	v_mov_b32_e32 v69, v2
	v_mov_b32_e32 v70, v2
	v_mov_b32_e32 v71, v2
	v_mov_b32_e32 v72, v2
	v_mov_b32_e32 v73, v2
	v_mov_b32_e32 v74, v2
	v_mov_b32_e32 v75, v2
	v_mov_b32_e32 v76, v2
	v_mov_b32_e32 v77, v2
	v_mov_b32_e32 v78, v2
	v_mov_b32_e32 v79, v2
	v_mov_b32_e32 v80, v2
	v_mov_b32_e32 v81, v2
	v_mov_b32_e32 v82, v2
	v_mov_b32_e32 v83, v2
	v_mov_b32_e32 v84, v2
	v_mov_b32_e32 v85, v2
	v_mov_b32_e32 v86, v2
	v_mov_b32_e32 v87, v2
	v_mov_b32_e32 v88, v2
	v_mov_b32_e32 v89, v2
	v_mov_b32_e32 v90, v2
	v_mov_b32_e32 v91, v2
	v_mov_b32_e32 v92, v2
	v_mov_b32_e32 v93, v2
	v_mov_b32_e32 v94, v2
	v_mov_b32_e32 v95, v2
	v_mov_b32_e32 v96, v2
	v_mov_b32_e32 v97, v2
	v_mov_b32_e32 v98, v2
	v_mov_b32_e32 v99, v2
	v_mov_b32_e32 v100, v2
	v_mov_b32_e32 v101, v2
	v_mov_b32_e32 v102, v2
	v_mov_b32_e32 v103, v2
	v_mov_b32_e32 v104, v2
	v_mov_b32_e32 v105, v2
	v_mov_b32_e32 v106, v2
	v_mov_b32_e32 v107, v2
	v_mov_b32_e32 v108, v2
	v_mov_b32_e32 v109, v2
	v_mov_b32_e32 v110, v2
	v_mov_b32_e32 v111, v2
	v_mov_b32_e32 v112, v2
	v_mov_b32_e32 v113, v2
	v_mov_b32_e32 v114, v2
	v_mov_b32_e32 v115, v2
	v_mov_b32_e32 v116, v2
	v_mov_b32_e32 v117, v2
	v_mov_b32_e32 v118, v2
	v_mov_b32_e32 v119, v2
	v_mov_b32_e32 v120, v2
	v_mov_b32_e32 v121, v2
	v_mov_b32_e32 v122, v2
	v_mov_b32_e32 v123, v2
	v_mov_b32_e32 v124, v2
	v_mov_b32_e32 v125, v2
	v_mov_b32_e32 v126, v2
	v_mov_b32_e32 v127, v2
	v_mov_b32_e32 v128, v2
	v_mov_b32_e32 v129, v2
	s_barrier

.LBB0_2362:
	s_or_b64 exec, exec, s[62:63]
	v_mov_b32_e32 v166, v0
	v_mov_b32_e32 v202, v0
	s_lshl_b32 s62, s64, 7
	v_lshlrev_b32_e32 v203, 2, v202
	v_and_b32_e32 v201, 0x7c, v203
	v_or_b32_e32 v172, s62, v201
	v_ashrrev_i32_e32 v173, 31, v172
	v_lshlrev_b64 v[10:11], 2, v[172:173]
	v_lshl_add_u64 v[2:3], s[50:51], 0, v[10:11]
	v_add_co_u32_e32 v6, vcc, 0x2000, v2
	v_lshl_add_u64 v[26:27], s[48:49], 0, v[10:11]
	s_nop 0
	v_addc_co_u32_e32 v7, vcc, 0, v3, vcc
	v_add_co_u32_e32 v14, vcc, 0x2000, v26
	v_ashrrev_i32_e32 v174, 2, v166
	s_nop 0
	v_addc_co_u32_e32 v15, vcc, 0, v27, vcc
	v_add_co_u32_e32 v18, vcc, 0x5000, v26
	v_and_b32_e32 v174, 0xffffffc0, v174
	s_nop 0
	v_addc_co_u32_e32 v19, vcc, 0, v27, vcc
	v_add_co_u32_e32 v22, vcc, 0x8000, v26
	v_and_b32_e32 v204, 15, v166
	s_nop 0
	v_addc_co_u32_e32 v23, vcc, 0, v27, vcc
	v_add_co_u32_e32 v28, vcc, 0xb000, v26
	v_add_u32_e32 v205, s60, v174
	s_nop 0
	v_addc_co_u32_e32 v29, vcc, 0, v27, vcc
	v_or_b32_e32 v176, v205, v204
	v_add_co_u32_e32 v30, vcc, 0xd000, v26
	v_ashrrev_i32_e32 v177, 31, v176
	v_add_u32_e32 v174, 0x80, v176
	v_addc_co_u32_e32 v31, vcc, 0, v27, vcc
	v_subrev_u32_e32 v178, s60, v176
	v_lshlrev_b32_e32 v178, 2, v178
	v_add_u32_e32 v178, 0x20010, v178
	v_ashrrev_i32_e32 v175, 31, v174
	global_load_dwordx4 v[2:5], v[2:3], off
	s_nop 0
	global_load_dwordx4 v[6:9], v[6:7], off offset:3072
	s_nop 0
	global_load_dwordx4 v[10:13], v[26:27], off
	s_nop 0
	global_load_dwordx4 v[14:17], v[14:15], off offset:3072
	s_nop 0
	global_load_dwordx4 v[18:21], v[18:19], off offset:2048
	s_nop 0
	global_load_dwordx4 v[22:25], v[22:23], off offset:1024
	s_nop 0
	global_load_dwordx4 v[26:29], v[28:29], off
	s_nop 0
	global_load_dwordx4 v[30:33], v[30:31], off offset:3072
	v_lshl_add_u64 v[180:181], v[174:175], 2, s[12:13]
	ds_read_b32 v174, v178
	ds_read_b32 v213, v178 offset:64
	ds_read_b32 v212, v178 offset:128
	ds_read_b32 v211, v178 offset:192
	ds_read_b32 v210, v178 offset:512
	ds_read_b32 v209, v178 offset:576
	ds_read_b32 v208, v178 offset:640
	ds_read_b32 v177, v178 offset:704
	v_subrev_co_u32_e32 v207, vcc, 14, v204
	s_xor_b64 s[64:65], vcc, -1
	v_cmp_lt_i32_e32 vcc, s75, v176
	s_and_b64 s[68:69], vcc, s[64:65]
	v_mov_b64_e32 v[178:179], 0
	s_and_saveexec_b64 s[66:67], s[68:69]
	v_add_u32_e32 v175, 0xffffc000, v205
	v_lshrrev_b32_e32 v175, 3, v175
	v_add_u32_e32 v175, v175, v207
	v_mov_b64_e32 v[178:179], s[8:9]
	v_mad_u64_u32 v[178:179], s[68:69], v175, s76, v[178:179]
	s_or_b64 exec, exec, s[66:67]
	s_waitcnt lgkmcnt(0)
	s_barrier
	v_fmamk_f32 v174, v174, 0x3a800000, v187
	v_mul_f32_e32 v175, 0x4b800000, v174
	v_cmp_gt_f32_e32 vcc, s77, v174
	s_movk_i32 s39, 0x60
	s_nop 0
	v_cndmask_b32_e32 v174, v174, v175, vcc
	v_rsq_f32_e32 v174, v174
	v_lshrrev_b32_e32 v175, 1, v166
	v_lshrrev_b32_e32 v166, 2, v166
	v_and_b32_e32 v166, 12, v166
	v_mul_f32_e32 v180, 0x45800000, v174
	v_cndmask_b32_e32 v180, v174, v180, vcc
	v_subrev_u32_e32 v174, s60, v176
	v_mul_lo_u32 v181, v174, s78
	v_and_or_b32 v166, v175, s39, v166
	v_add_u32_e32 v215, 16, v181
	v_lshlrev_b32_e32 v206, 1, v166
	v_pk_mul_f32 v[158:159], v[158:159], v[180:181] op_sel_hi:[1,0]
	v_add_u32_e32 v214, v215, v206
	v_cvt_pk_bf16_f32 v174, v158, v159
	v_pk_mul_f32 v[160:161], v[160:161], v[180:181] op_sel_hi:[1,0]
	v_cmp_ne_u64_e32 vcc, 0, v[178:179]
	v_cvt_pk_bf16_f32 v175, v160, v161
	ds_write_b64 v214, v[174:175]
	v_or_b32_e32 v174, s62, v166
	v_ashrrev_i32_e32 v175, 31, v174
	s_and_saveexec_b64 s[66:67], vcc
	s_cbranch_execz .LBB0_2366
	v_lshl_add_u64 v[216:217], v[174:175], 2, v[178:179]
	global_store_dwordx4 v[216:217], v[158:161], off

.LBB0_2454:
	s_or_b64 exec, exec, s[60:61]
	v_cmp_gt_i32_e32 vcc, s74, v202
	s_waitcnt vmcnt(0) lgkmcnt(0)
	s_barrier
	s_and_saveexec_b64 s[60:61], vcc
	s_cbranch_execz .LBB0_2456
	v_ashrrev_i32_e32 v36, 6, v202
	v_add_u32_e32 v34, 0xfc, v36
	v_cmp_gt_i32_e32 vcc, 2, v36
	v_lshlrev_b32_e32 v35, 1, v203
	v_and_b32_e32 v166, 0x1f8, v35
	v_cndmask_b32_e32 v34, v34, v36, vcc
	v_mul_lo_u32 v34, v34, s78
	v_add3_u32 v34, 16, v34, v166
	ds_read_b64 v[34:35], v34
	v_lshl_add_u32 v38, s85, 2, v36
	v_mov_b64_e32 v[36:37], s[40:41]
	v_mad_i64_i32 v[36:37], s[62:63], v38, s81, v[36:37]
	v_lshl_add_u64 v[36:37], s[58:59], 1, v[36:37]
	v_lshl_add_u64 v[36:37], v[36:37], 0, v[166:167]
	s_waitcnt lgkmcnt(0)
	global_store_dwordx2 v[36:37], v[34:35], off
